# attention: query loads issued at the top of the item together with key rope loads; single vmcnt(0) covers K/V + rope + Q
# baseline (speedup 1.0000x reference)
; #define LAS __attribute__((address_space(3)))
; __device__ __forceinline__ void p4_attn(const Params& p, LAS unsigned char* lds, const int dummy) {
;     ...
;         {
;             const int row = tid >> 1, pv = tid & 1; const int jk = blk * 128 - 128 + row;
;             u32x4 o1 = kr[0], o2 = kr[1];
;             if (jk >= 0) {
;                 const int pos = jk * dil + rr;
;                 float x1[8], x2[8]; unpack8(kr[0], x1); unpack8(kr[1], x2);
;                 const float4 ca = *(const float4*)(RC + pos * 16 + 8 * pv), cb = *(const float4*)(RC + pos * 16 + 8 * pv + 4);
;                 const float4 sa = *(const float4*)(RS + pos * 16 + 8 * pv), sb = *(const float4*)(RS + pos * 16 + 8 * pv + 4);
;                 const float cc[8] = {ca.x, ca.y, ca.z, ca.w, cb.x, cb.y, cb.z, cb.w}, sn[8] = {sa.x, sa.y, sa.z, sa.w, sb.x, sb.y, sb.z, sb.w};
;                 float y1[8], y2[8];
; #pragma unroll
;                 for (int e = 0; e < 8; ++e) { y1[e] = x1[e] * cc[e] - x2[e] * sn[e]; y2[e] = x2[e] * cc[e] + x1[e] * sn[e]; }
;                 o1 = pack8(y1); o2 = pack8(y2);
;             }
;             *(LAS u32x4*)(KA + row * KA_STRIDE + (8 * pv) * 2) = o1;
;             *(LAS u32x4*)(KA + row * KA_STRIDE + (16 + 8 * pv) * 2) = o2;
; #pragma unroll
;             for (int i = 0; i < 6; ++i) { const int task = tid + 512 * i; const int row2 = task / 12, v = 4 + task % 12; *(LAS u32x4*)(KA + row2 * KA_STRIDE + v * 16) = kr[2 + i]; }
; #pragma unroll
;             for (int vi = 0; vi < 8; ++vi) *(LAS u32x4*)(VB + row * VB_STRIDE + (pv * 64 + vi * 8) * 2) = vr[vi];
;         }
;         const int ql = 16 * wid + r; const int jq = blk * 128 + ql; const int posq = jq * dil + rr; const size_t tq = (size_t)(tokb + posq);
;         bf16x8 qf[4];
;         {
;             bf16_t* qsrc = R1 + tq * QZ_LD + qcol;
; #pragma unroll
;             for (int kk = 0; kk < 4; ++kk) {
;                 const u32x4 av = *(const u32x4*)(qsrc + 32 * kk + 8 * q);
;                 float x[8]; unpack8(av, x);
;                 if (kk == 0) {
;                     const int fi = 8 * (q & 1);
;                     const float4 ca = *(const float4*)(RC + posq * 16 + fi), cb = *(const float4*)(RC + posq * 16 + fi + 4);
;                     const float4 sa = *(const float4*)(RS + posq * 16 + fi), sb = *(const float4*)(RS + posq * 16 + fi + 4);
.LBB0_592:
	s_ashr_i32 s1, s8, 6
	s_mul_hi_i32 s4, s1, 0x55555556
	s_lshr_b32 s5, s4, 31
	s_add_i32 s4, s4, s5
	s_mul_i32 s4, s4, 3
	s_sub_i32 s9, s1, s4
	s_lshl_b32 s4, s9, 1
	s_lshr_b32 s1, 16, s4
	s_and_b32 s0, s8, 15
	s_add_i32 s1, s1, -1
	s_and_b32 s81, s1, s0
	s_lshl_b32 s11, s81, 7
	s_sub_i32 s1, 4, s4
	s_lshr_b32 s5, s0, s1
	s_mul_hi_i32 s0, s8, 0x2aaaaaab
	v_add_u32_e32 v37, s11, v145
	s_lshr_b32 s1, s0, 31
	s_lshr_b32 s0, s0, 5
	v_lshlrev_b32_e32 v37, s4, v37
	s_add_i32 s1, s0, s1
	v_add_u32_e32 v37, s5, v37
	s_bfe_u32 s10, s8, 0x20004
	v_lshl_add_u32 v124, s1, 11, v37
	s_lshl_b32 s0, s9, 9
	s_lshl_b32 s6, s10, 7
	v_ashrrev_i32_e32 v125, 31, v124
	v_readlane_b32 s98, v254, 20
	s_or_b32 s0, s0, s6
	v_lshlrev_b64 v[38:39], 12, v[124:125]
	v_readlane_b32 s99, v254, 21
	s_ashr_i32 s1, s0, 31
	v_mov_b32_e32 v121, v36
	v_lshl_add_u64 v[38:39], s[98:99], 0, v[38:39]
	v_lshl_add_u64 v[126:127], s[0:1], 1, v[38:39]
	v_lshlrev_b32_e32 v68, 4, v37
	v_mov_b32_e32 v69, v36
	v_lshl_add_u64 v[38:39], v[126:127], 0, v[120:121]
	v_lshlrev_b64 v[68:69], 2, v[68:69]
	global_load_dwordx4 v[108:111], v[38:39], off
	v_lshl_add_u64 v[70:71], v[118:119], 0, v[68:69]
	v_lshl_add_u64 v[68:69], v[116:117], 0, v[68:69]
	global_load_dwordx4 v[80:83], v[68:69], off offset:16
	global_load_dwordx4 v[88:91], v[68:69], off
	global_load_dwordx4 v[84:87], v[70:71], off offset:16
	global_load_dwordx4 v[92:95], v[70:71], off
	global_load_dwordx4 v[76:79], v[38:39], off offset:64
	global_load_dwordx4 v[72:75], v[38:39], off offset:128
	s_nop 0
	global_load_dwordx4 v[68:71], v[38:39], off offset:192
	v_add_u32_e32 v37, s11, v144
	v_cmp_lt_i32_e32 vcc, -1, v37
	s_and_saveexec_b64 s[0:1], vcc
	s_cbranch_execz .Lat_norope
	v_lshlrev_b32_e32 v37, s4, v37
	v_add_lshl_u32 v38, v37, s5, 4
	v_mov_b32_e32 v39, v36
	v_lshlrev_b64 v[38:39], 2, v[38:39]
	v_lshl_add_u64 v[218:219], v[112:113], 0, v[38:39]
	v_lshl_add_u64 v[38:39], v[114:115], 0, v[38:39]
	global_load_dwordx4 v[214:217], v[218:219], off offset:16
	s_nop 0
	global_load_dwordx4 v[218:221], v[218:219], off
	s_nop 0
	global_load_dwordx4 v[222:225], v[38:39], off offset:16
	global_load_dwordx4 v[226:229], v[38:39], off
.Lat_norope:
	s_or_b64 exec, exec, s[0:1]
	s_waitcnt vmcnt(0)
	v_mov_b64_e32 v[102:103], v[6:7]
	v_mov_b64_e32 v[98:99], v[2:3]
	v_mov_b64_e32 v[100:101], v[4:5]
	v_mov_b64_e32 v[96:97], v[0:1]
	s_and_saveexec_b64 s[0:1], vcc
	s_cbranch_execz .LBB0_594
	v_lshlrev_b32_e32 v230, 16, v0
	v_and_b32_e32 v231, 0xffff0000, v0
	v_lshlrev_b32_e32 v232, 16, v4
	v_and_b32_e32 v233, 0xffff0000, v4
	v_pk_mul_f32 v[38:39], v[226:227], v[230:231]
	v_pk_mul_f32 v[226:227], v[226:227], v[232:233]
	v_pk_fma_f32 v[38:39], v[218:219], v[232:233], v[38:39]
	v_pk_fma_f32 v[218:219], v[218:219], v[230:231], v[226:227] neg_lo:[0,0,1] neg_hi:[0,0,1]
	v_lshlrev_b32_e32 v226, 16, v1
	v_and_b32_e32 v227, 0xffff0000, v1
	v_lshlrev_b32_e32 v230, 16, v5
	v_and_b32_e32 v231, 0xffff0000, v5
	v_pk_mul_f32 v[232:233], v[228:229], v[226:227]
	v_pk_mul_f32 v[228:229], v[228:229], v[230:231]
	v_pk_fma_f32 v[232:233], v[220:221], v[230:231], v[232:233]
	v_pk_fma_f32 v[220:221], v[220:221], v[226:227], v[228:229] neg_lo:[0,0,1] neg_hi:[0,0,1]
	v_lshlrev_b32_e32 v226, 16, v2
	v_and_b32_e32 v227, 0xffff0000, v2
	v_lshlrev_b32_e32 v228, 16, v6
	v_and_b32_e32 v229, 0xffff0000, v6
	v_pk_mul_f32 v[230:231], v[222:223], v[226:227]
	v_pk_mul_f32 v[222:223], v[222:223], v[228:229]
	v_pk_fma_f32 v[230:231], v[214:215], v[228:229], v[230:231]
	v_pk_fma_f32 v[214:215], v[214:215], v[226:227], v[222:223] neg_lo:[0,0,1] neg_hi:[0,0,1]
	v_lshlrev_b32_e32 v222, 16, v3
	v_and_b32_e32 v223, 0xffff0000, v3
	v_lshlrev_b32_e32 v226, 16, v7
	v_and_b32_e32 v227, 0xffff0000, v7
	v_pk_mul_f32 v[228:229], v[224:225], v[222:223]
	v_pk_mul_f32 v[224:225], v[224:225], v[226:227]
	v_pk_fma_f32 v[228:229], v[216:217], v[226:227], v[228:229]
	v_pk_fma_f32 v[216:217], v[216:217], v[222:223], v[224:225] neg_lo:[0,0,1] neg_hi:[0,0,1]
	v_cvt_pk_bf16_f32 v96, v218, v219
	v_cvt_pk_bf16_f32 v97, v220, v221
	v_cvt_pk_bf16_f32 v98, v214, v215
	v_cvt_pk_bf16_f32 v99, v216, v217
	v_cvt_pk_bf16_f32 v100, v38, v39
	v_cvt_pk_bf16_f32 v101, v232, v233
	v_cvt_pk_bf16_f32 v102, v230, v231
	v_cvt_pk_bf16_f32 v103, v228, v229
.LBB0_594:
	s_or_b64 exec, exec, s[0:1]
	ds_write_b128 v172, v[96:99]
	ds_write_b128 v172, v[100:103] offset:32
	ds_write_b128 v173, v[8:11] offset:64
	ds_write_b128 v174, v[12:15] offset:64
	ds_write_b128 v175, v[16:19] offset:64
	ds_write_b128 v176, v[24:27] offset:64
	ds_write_b128 v177, v[28:31] offset:64
	ds_write_b128 v178, v[32:35] offset:64
	ds_write_b128 v179, v[20:23]
	ds_write_b128 v179, v[40:43] offset:16
	ds_write_b128 v179, v[48:51] offset:32
	ds_write_b128 v179, v[44:47] offset:48
	ds_write_b128 v179, v[52:55] offset:64
	ds_write_b128 v179, v[56:59] offset:80
	ds_write_b128 v179, v[64:67] offset:96
	ds_write_b128 v179, v[60:63] offset:112
	v_readlane_b32 s0, v254, 51
	s_add_i32 s8, s8, s0
	s_cmpk_gt_i32 s8, 0x5ff
	s_cselect_b64 s[86:87], -1, 0
	s_and_b64 vcc, exec, s[86:87]
	v_readlane_b32 s1, v254, 52
	s_waitcnt lgkmcnt(0)
	s_barrier
	s_waitcnt vmcnt(7)
	v_lshlrev_b32_e32 v106, 16, v108
	v_and_b32_e32 v107, 0xffff0000, v108
	v_lshlrev_b32_e32 v102, 16, v109
	v_and_b32_e32 v103, 0xffff0000, v109
	v_lshlrev_b32_e32 v98, 16, v110
	v_and_b32_e32 v99, 0xffff0000, v110
	v_lshlrev_b32_e32 v96, 16, v111
	v_and_b32_e32 v97, 0xffff0000, v111
	ds_bpermute_b32 v110, v147, v106
	ds_bpermute_b32 v111, v147, v107
	ds_bpermute_b32 v108, v147, v102
	ds_bpermute_b32 v109, v147, v103
	ds_bpermute_b32 v104, v147, v98
	ds_bpermute_b32 v105, v147, v99
	ds_bpermute_b32 v100, v147, v96
	ds_bpermute_b32 v101, v147, v97
